# stack on v11: diff prologue load batching + diff finalize DPP all-reduce + RG-LRU hardware sqrt
# speedup vs baseline: 1.0063x; 1.0063x over previous
; #define LAS __attribute__((address_space(3)))
; __device__ __forceinline__ float fast_exp2(float x) { return __builtin_amdgcn_exp2f(x); }
; __device__ __forceinline__ float sigmoidf_(float x) { return fast_rcp(1.0f + fast_exp2(-x * LOG2E)); }
; __device__ __forceinline__ int crow(int r, int hi) { return (r & 3) + 8 * (r >> 2) + 4 * hi; }
; __device__ __forceinline__ void rglru_unit(const Params& P, int l, int unit, LAS unsigned char* lds, bool dry = false) {
;     ...
;         bf16_t* gp = proj + O_GR + (rowb + t0 + 16 * ss) * XP + 128 * n + 64 * j + sc;
;         unsigned short gq[16];
; #pragma unroll
;         for (int k = 0; k < 16; ++k) gq[k] = gp[(size_t)k * XP];
;         __syncthreads();
;         f32x16 accr = {}, acci = {};
; #pragma unroll
;         for (int s = 0; s < 8; ++s) { const bf16x8 a = *(const LAS bf16x8*)(xc + (32 * tb + r32) * 272 + (16 * s + 8 * hi) * 2);
;             const bf16x8 wr_ = *(const LAS bf16x8*)(WB + (32 * cb + r32) * 272 + (16 * s + 8 * hi) * 2), wi_ = *(const LAS bf16x8*)(WB + (64 + 32 * cb + r32) * 272 + (16 * s + 8 * hi) * 2);
;             accr = __builtin_amdgcn_mfma_f32_32x32x16_bf16(a, wr_, accr, 0, 0, 0); acci = __builtin_amdgcn_mfma_f32_32x32x16_bf16(a, wi_, acci, 0, 0, 0); }
; #pragma unroll
;         for (int r = 0; r < 16; ++r) { const int tok = 32 * tb + crow(r, hi);
;             const float rr = sigmoidf_(accr[r] + br), ii = sigmoidf_(acci[r] + bi);
;             const float la = -rr * sp8; const float a = fast_exp2(la * LOG2E);
;             const float x2 = 2.0f * la;
;             const float em = -x2 * (1.0f + x2 * (0.5f + x2 * (0.16666667f + x2 * (0.041666668f + x2 * (0.0083333338f + x2 * 0.0013888889f)))));
;             const float mult = __builtin_sqrtf(fmaxf(em, 0.f));
;             const float xcv = bf2f(*(const LAS unsigned short*)(xc + tok * 272 + dch * 2));
;             Ab[tok * 64 + 32 * cb + r32] = a; Ub[tok * 64 + 32 * cb + r32] = mult * ii * xcv; }
.LBB0_367:
	v_lshl_add_u64 v[2:3], v[108:109], 0, s[22:23]
	v_add_co_u32_e32 v126, vcc, 0xae00000, v2
	s_add_u32 s22, s22, 0x40000
	s_nop 0
	v_addc_co_u32_e32 v127, vcc, 0, v3, vcc
	v_add_co_u32_e32 v124, vcc, 0xae01000, v2
	s_addc_u32 s23, s23, 0
	s_nop 0
	v_addc_co_u32_e32 v125, vcc, 0, v3, vcc
	v_add_co_u32_e32 v122, vcc, 0xae02000, v2
	s_cmp_lg_u32 s22, 0x400000
	s_nop 0
	v_addc_co_u32_e32 v123, vcc, 0, v3, vcc
	v_add_co_u32_e32 v120, vcc, 0xae03000, v2
	v_add_u32_e32 v110, 0x80, v110
	s_nop 0
	v_addc_co_u32_e32 v121, vcc, 0, v3, vcc
	v_add_co_u32_e32 v118, vcc, 0xae04000, v2
	global_load_ushort v207, v[126:127], off
	global_load_ushort v206, v[126:127], off offset:2048
	global_load_ushort v205, v[124:125], off
	global_load_ushort v204, v[124:125], off offset:2048
	global_load_ushort v203, v[122:123], off
	global_load_ushort v202, v[122:123], off offset:2048
	global_load_ushort v201, v[120:121], off
	global_load_ushort v200, v[120:121], off offset:2048
	v_addc_co_u32_e32 v119, vcc, 0, v3, vcc
	v_add_co_u32_e32 v116, vcc, 0xae05000, v2
	s_nop 1
	v_addc_co_u32_e32 v117, vcc, 0, v3, vcc
	v_add_co_u32_e32 v114, vcc, 0xae06000, v2
	s_nop 1
	v_addc_co_u32_e32 v115, vcc, 0, v3, vcc
	v_add_co_u32_e32 v112, vcc, 0xae07000, v2
	s_nop 1
	v_addc_co_u32_e32 v113, vcc, 0, v3, vcc
	global_load_ushort v199, v[118:119], off
	global_load_ushort v198, v[118:119], off offset:2048
	global_load_ushort v197, v[116:117], off
	global_load_ushort v196, v[116:117], off offset:2048
	global_load_ushort v195, v[114:115], off
	global_load_ushort v194, v[114:115], off offset:2048
	global_load_ushort v111, v[112:113], off
	global_load_ushort v1, v[112:113], off offset:2048
	s_waitcnt lgkmcnt(0)
	s_barrier
	ds_read_b128 v[2:5], v190
	ds_read_b128 v[6:9], v191
	s_waitcnt lgkmcnt(0)
	v_mfma_f32_32x32x16_bf16 v[18:33], v[2:5], v[6:9], 0
	ds_read_b128 v[6:9], v192
	ds_read_b128 v[208:211], v190 offset:32
	ds_read_b128 v[212:215], v191 offset:32
	s_waitcnt lgkmcnt(2)
	v_mfma_f32_32x32x16_bf16 v[2:17], v[2:5], v[6:9], 0
	s_waitcnt lgkmcnt(0)
	v_mfma_f32_32x32x16_bf16 v[18:33], v[208:211], v[212:215], v[18:33]
	ds_read_b128 v[212:215], v192 offset:32
	s_waitcnt lgkmcnt(0)
	v_mfma_f32_32x32x16_bf16 v[2:17], v[208:211], v[212:215], v[2:17]
	ds_read_b128 v[208:211], v190 offset:64
	ds_read_b128 v[212:215], v191 offset:64
	s_waitcnt lgkmcnt(0)
	v_mfma_f32_32x32x16_bf16 v[18:33], v[208:211], v[212:215], v[18:33]
	ds_read_b128 v[212:215], v192 offset:64
	s_waitcnt lgkmcnt(0)
	v_mfma_f32_32x32x16_bf16 v[2:17], v[208:211], v[212:215], v[2:17]
	ds_read_b128 v[208:211], v190 offset:96
	ds_read_b128 v[212:215], v191 offset:96
	s_waitcnt lgkmcnt(0)
	v_mfma_f32_32x32x16_bf16 v[18:33], v[208:211], v[212:215], v[18:33]
	ds_read_b128 v[212:215], v192 offset:96
	s_waitcnt lgkmcnt(0)
	v_mfma_f32_32x32x16_bf16 v[2:17], v[208:211], v[212:215], v[2:17]
	ds_read_b128 v[208:211], v190 offset:128
	ds_read_b128 v[212:215], v191 offset:128
	s_waitcnt lgkmcnt(0)
	v_mfma_f32_32x32x16_bf16 v[18:33], v[208:211], v[212:215], v[18:33]
	ds_read_b128 v[212:215], v192 offset:128
	s_waitcnt lgkmcnt(0)
	v_mfma_f32_32x32x16_bf16 v[2:17], v[208:211], v[212:215], v[2:17]
	ds_read_b128 v[208:211], v190 offset:160
	ds_read_b128 v[212:215], v191 offset:160
	s_waitcnt lgkmcnt(0)
	v_mfma_f32_32x32x16_bf16 v[18:33], v[208:211], v[212:215], v[18:33]
	ds_read_b128 v[212:215], v192 offset:160
	s_waitcnt lgkmcnt(0)
	v_mfma_f32_32x32x16_bf16 v[2:17], v[208:211], v[212:215], v[2:17]
	ds_read_b128 v[208:211], v190 offset:192
	ds_read_b128 v[212:215], v191 offset:192
	s_waitcnt lgkmcnt(0)
	v_mfma_f32_32x32x16_bf16 v[18:33], v[208:211], v[212:215], v[18:33]
	ds_read_b128 v[212:215], v192 offset:192
	s_waitcnt lgkmcnt(0)
	v_mfma_f32_32x32x16_bf16 v[2:17], v[208:211], v[212:215], v[2:17]
	ds_read_b128 v[208:211], v190 offset:224
	ds_read_b128 v[212:215], v191 offset:224
	ds_read_b128 v[226:229], v192 offset:224
	s_waitcnt lgkmcnt(1)
	v_mfma_f32_32x32x16_bf16 v[18:33], v[208:211], v[212:215], v[18:33]
	s_waitcnt lgkmcnt(0)
	v_mfma_f32_32x32x16_bf16 v[2:17], v[208:211], v[226:229], v[2:17]
	s_nop 9
	v_add_f32_e32 v18, v128, v18
	v_mul_f32_e32 v18, 0xbfb8aa3b, v18
	v_exp_f32_e32 v18, v18
	v_add_f32_e32 v19, v128, v19
	v_mul_f32_e32 v19, 0xbfb8aa3b, v19
	v_exp_f32_e32 v19, v19
	v_add_f32_e32 v18, 1.0, v18
	v_rcp_f32_e64 v18, -v18
	v_add_f32_e32 v2, v129, v2
	v_mul_f32_e32 v2, 0xbfb8aa3b, v2
	v_exp_f32_e32 v2, v2
	v_mul_f32_e32 v18, v130, v18
	v_add_f32_e32 v86, v18, v18
	v_fmamk_f32 v87, v86, 0x3ab60b61, v218
	v_fmaak_f32 v87, v86, v87, 0x3d2aaaab
	v_fmaak_f32 v87, v86, v87, 0x3e2aaaab
	v_fma_f32 v87, v86, v87, 0.5
	v_fma_f32 v87, v86, v87, 1.0
	v_mul_f32_e64 v86, v87, -v86
	v_max_f32_e32 v86, 0, v86
	v_mul_f32_e32 v18, 0x3fb8aa3b, v18
	v_exp_f32_e32 v18, v18
	v_add_f32_e32 v2, 1.0, v2
	v_rcp_f32_e32 v2, v2
	v_add_f32_e32 v3, v129, v3
	v_mul_f32_e32 v3, 0xbfb8aa3b, v3
	v_exp_f32_e32 v3, v3
	v_add_f32_e32 v4, v129, v4
	v_mul_f32_e32 v4, 0xbfb8aa3b, v4
	v_exp_f32_e32 v4, v4
	v_sqrt_f32_e32 v86, v86
	ds_read_u16 v87, v193
	ds_read_u16 v88, v193 offset:272
	ds_read_u16 v182, v193 offset:544
	ds_read_u16 v183, v193 offset:816
	ds_read_u16 v184, v193 offset:2176
	ds_read_u16 v185, v193 offset:2448
	ds_read_u16 v208, v193 offset:2720
	ds_read_u16 v209, v193 offset:2992
	ds_write_b32 v134, v18 offset:34816
	v_add_f32_e32 v18, 1.0, v19
	v_rcp_f32_e64 v18, -v18
	s_waitcnt lgkmcnt(8)
; #define LAS __attribute__((address_space(3)))
; __device__ __forceinline__ float fast_exp2(float x) { return __builtin_amdgcn_exp2f(x); }
; __device__ __forceinline__ float sigmoidf_(float x) { return fast_rcp(1.0f + fast_exp2(-x * LOG2E)); }
; __device__ __forceinline__ int crow(int r, int hi) { return (r & 3) + 8 * (r >> 2) + 4 * hi; }
; __device__ __forceinline__ void rglru_unit(const Params& P, int l, int unit, LAS unsigned char* lds, bool dry = false) {
;     ...
;         for (int r = 0; r < 16; ++r) { const int tok = 32 * tb + crow(r, hi);
;             const float rr = sigmoidf_(accr[r] + br), ii = sigmoidf_(acci[r] + bi);
;             const float la = -rr * sp8; const float a = fast_exp2(la * LOG2E);
;             const float x2 = 2.0f * la;
;             const float em = -x2 * (1.0f + x2 * (0.5f + x2 * (0.16666667f + x2 * (0.041666668f + x2 * (0.0083333338f + x2 * 0.0013888889f)))));
;             const float mult = __builtin_sqrtf(fmaxf(em, 0.f));
;             const float xcv = bf2f(*(const LAS unsigned short*)(xc + tok * 272 + dch * 2));
;             Ab[tok * 64 + 32 * cb + r32] = a; Ub[tok * 64 + 32 * cb + r32] = mult * ii * xcv; }
	v_lshlrev_b32_e32 v87, 16, v87
	v_mul_f32_e32 v2, v2, v86
	v_mul_f32_e32 v2, v2, v87
	ds_write_b32 v135, v2
	v_add_f32_e32 v2, 1.0, v3
	v_mul_f32_e32 v3, v130, v18
	v_add_f32_e32 v18, v3, v3
	v_fmamk_f32 v19, v18, 0x3ab60b61, v218
	v_fmaak_f32 v19, v18, v19, 0x3d2aaaab
	v_fmaak_f32 v19, v18, v19, 0x3e2aaaab
	v_fma_f32 v19, v18, v19, 0.5
	v_fma_f32 v19, v18, v19, 1.0
	v_mul_f32_e64 v18, v19, -v18
	v_max_f32_e32 v18, 0, v18
	v_mul_f32_e32 v3, 0x3fb8aa3b, v3
	v_exp_f32_e32 v3, v3
	v_rcp_f32_e32 v2, v2
	ds_write_b32 v136, v3 offset:34816
	s_nop 0
	s_nop 1
	v_sqrt_f32_e32 v18, v18
	v_add_f32_e32 v19, v128, v20
	v_mul_f32_e32 v19, 0xbfb8aa3b, v19
	v_exp_f32_e32 v19, v19
	s_waitcnt lgkmcnt(9)
	v_lshlrev_b32_e32 v20, 16, v88
	v_mul_f32_e32 v2, v2, v18
	v_mul_f32_e32 v2, v2, v20
	v_add_f32_e32 v3, 1.0, v19
	v_rcp_f32_e64 v3, -v3
	ds_write_b32 v137, v2
	v_add_f32_e32 v2, 1.0, v4
	v_rcp_f32_e32 v2, v2
	v_mul_f32_e32 v3, v130, v3
	v_add_f32_e32 v4, v3, v3
	v_fmamk_f32 v18, v4, 0x3ab60b61, v218
	v_fmaak_f32 v18, v4, v18, 0x3d2aaaab
	v_fmaak_f32 v18, v4, v18, 0x3e2aaaab
	v_fma_f32 v18, v4, v18, 0.5
	v_fma_f32 v18, v4, v18, 1.0
	v_mul_f32_e64 v4, v18, -v4
	v_max_f32_e32 v4, 0, v4
	v_mul_f32_e32 v3, 0x3fb8aa3b, v3
	v_exp_f32_e32 v3, v3
	ds_write_b32 v138, v3 offset:34816
	s_nop 0
	s_waitcnt lgkmcnt(10)
	v_lshlrev_b32_e32 v19, 16, v182
	v_sqrt_f32_e32 v4, v4
	v_add_f32_e32 v18, v128, v21
	v_mul_f32_e32 v18, 0xbfb8aa3b, v18
	v_exp_f32_e32 v18, v18
	v_mul_f32_e32 v2, v2, v4
	v_add_f32_e32 v4, v129, v5
	v_mul_f32_e32 v4, 0xbfb8aa3b, v4
	v_add_f32_e32 v3, 1.0, v18
	v_rcp_f32_e64 v3, -v3
	v_exp_f32_e32 v4, v4
	v_mul_f32_e32 v2, v2, v19
	ds_write_b32 v139, v2
	v_mul_f32_e32 v3, v130, v3
	v_add_f32_e32 v2, 1.0, v4
	v_add_f32_e32 v4, v3, v3
	v_fmamk_f32 v5, v4, 0x3ab60b61, v218
	v_fmaak_f32 v5, v4, v5, 0x3d2aaaab
	v_fmaak_f32 v5, v4, v5, 0x3e2aaaab
	v_fma_f32 v5, v4, v5, 0.5
	v_fma_f32 v5, v4, v5, 1.0
	v_mul_f32_e64 v4, v5, -v4
	v_max_f32_e32 v4, 0, v4
	v_mul_f32_e32 v3, 0x3fb8aa3b, v3
	v_rcp_f32_e32 v2, v2
	v_exp_f32_e32 v3, v3
	ds_write_b32 v140, v3 offset:34816
	s_waitcnt lgkmcnt(11)
	v_lshlrev_b32_e32 v18, 16, v183
	v_sqrt_f32_e32 v4, v4
	v_add_f32_e32 v5, v128, v22
	v_mul_f32_e32 v5, 0xbfb8aa3b, v5
	v_exp_f32_e32 v5, v5
	v_mul_f32_e32 v2, v2, v4
	v_add_f32_e32 v4, v129, v6
	v_mul_f32_e32 v4, 0xbfb8aa3b, v4
	v_add_f32_e32 v3, 1.0, v5
	v_rcp_f32_e64 v3, -v3
	v_exp_f32_e32 v4, v4
	v_mul_f32_e32 v2, v2, v18
	ds_write_b32 v141, v2
	v_mul_f32_e32 v3, v130, v3
	v_add_f32_e32 v2, 1.0, v4
	v_add_f32_e32 v4, v3, v3
	v_fmamk_f32 v5, v4, 0x3ab60b61, v218
	v_fmaak_f32 v5, v4, v5, 0x3d2aaaab
	v_fmaak_f32 v5, v4, v5, 0x3e2aaaab
	v_fma_f32 v5, v4, v5, 0.5
	v_fma_f32 v5, v4, v5, 1.0
	v_mul_f32_e64 v4, v5, -v4
	v_max_f32_e32 v4, 0, v4
	v_mul_f32_e32 v3, 0x3fb8aa3b, v3
	v_rcp_f32_e32 v2, v2
	v_exp_f32_e32 v3, v3
	ds_write_b32 v142, v3 offset:34816
	s_waitcnt lgkmcnt(12)
	v_lshlrev_b32_e32 v6, 16, v184
	v_sqrt_f32_e32 v4, v4
	v_add_f32_e32 v5, v128, v23
	v_mul_f32_e32 v5, 0xbfb8aa3b, v5
	v_exp_f32_e32 v5, v5
	v_mul_f32_e32 v2, v2, v4
	v_add_f32_e32 v4, v129, v7
	v_mul_f32_e32 v4, 0xbfb8aa3b, v4
	v_add_f32_e32 v3, 1.0, v5
	v_rcp_f32_e64 v3, -v3
	v_exp_f32_e32 v4, v4
	v_mul_f32_e32 v2, v2, v6
	ds_write_b32 v143, v2
	v_mul_f32_e32 v3, v130, v3
	v_add_f32_e32 v2, 1.0, v4
	v_add_f32_e32 v4, v3, v3
	v_fmamk_f32 v5, v4, 0x3ab60b61, v218
	v_fmaak_f32 v5, v4, v5, 0x3d2aaaab
	v_fmaak_f32 v5, v4, v5, 0x3e2aaaab
	v_fma_f32 v5, v4, v5, 0.5
	v_fma_f32 v5, v4, v5, 1.0
	v_mul_f32_e64 v4, v5, -v4
	v_max_f32_e32 v4, 0, v4
	v_mul_f32_e32 v3, 0x3fb8aa3b, v3
	v_rcp_f32_e32 v2, v2
	v_exp_f32_e32 v3, v3
	ds_write_b32 v144, v3 offset:34816
	s_waitcnt lgkmcnt(13)
	v_lshlrev_b32_e32 v6, 16, v185
	v_sqrt_f32_e32 v4, v4
	v_add_f32_e32 v5, v128, v24
	v_mul_f32_e32 v5, 0xbfb8aa3b, v5
	v_exp_f32_e32 v5, v5
	v_mul_f32_e32 v2, v2, v4
	v_add_f32_e32 v4, v129, v8
	v_mul_f32_e32 v4, 0xbfb8aa3b, v4
	v_add_f32_e32 v3, 1.0, v5
	v_rcp_f32_e64 v3, -v3
	v_exp_f32_e32 v4, v4
	v_mul_f32_e32 v2, v2, v6
	ds_write_b32 v145, v2
	v_mul_f32_e32 v3, v130, v3
	v_add_f32_e32 v2, 1.0, v4
	v_add_f32_e32 v4, v3, v3
	v_fmamk_f32 v5, v4, 0x3ab60b61, v218
	v_fmaak_f32 v5, v4, v5, 0x3d2aaaab
	v_fmaak_f32 v5, v4, v5, 0x3e2aaaab
	v_fma_f32 v5, v4, v5, 0.5
	v_fma_f32 v5, v4, v5, 1.0
	v_mul_f32_e64 v4, v5, -v4
	v_max_f32_e32 v4, 0, v4
	v_mul_f32_e32 v3, 0x3fb8aa3b, v3
	v_rcp_f32_e32 v2, v2
	v_exp_f32_e32 v3, v3
	ds_write_b32 v146, v3 offset:34816
	s_waitcnt lgkmcnt(14)
	v_lshlrev_b32_e32 v6, 16, v208
	v_sqrt_f32_e32 v4, v4
	v_add_f32_e32 v5, v128, v25
	v_mul_f32_e32 v5, 0xbfb8aa3b, v5
	v_exp_f32_e32 v5, v5
	v_mul_f32_e32 v2, v2, v4
	v_add_f32_e32 v4, v129, v9
	v_mul_f32_e32 v4, 0xbfb8aa3b, v4
	v_add_f32_e32 v3, 1.0, v5
	v_rcp_f32_e64 v3, -v3
	v_exp_f32_e32 v4, v4
	v_mul_f32_e32 v2, v2, v6
	ds_write_b32 v147, v2
	v_mul_f32_e32 v3, v130, v3
	v_add_f32_e32 v2, 1.0, v4
	v_add_f32_e32 v4, v3, v3
	v_fmamk_f32 v5, v4, 0x3ab60b61, v218
	v_fmaak_f32 v5, v4, v5, 0x3d2aaaab
	v_fmaak_f32 v5, v4, v5, 0x3e2aaaab
	v_fma_f32 v5, v4, v5, 0.5
	v_fma_f32 v5, v4, v5, 1.0
	v_mul_f32_e64 v4, v5, -v4
	v_max_f32_e32 v4, 0, v4
	v_mul_f32_e32 v3, 0x3fb8aa3b, v3
	v_rcp_f32_e32 v2, v2
	v_exp_f32_e32 v3, v3
	ds_write_b32 v148, v3 offset:34816
	s_waitcnt lgkmcnt(14)
; #define LAS __attribute__((address_space(3)))
; __device__ __forceinline__ float fast_exp2(float x) { return __builtin_amdgcn_exp2f(x); }
; __device__ __forceinline__ float sigmoidf_(float x) { return fast_rcp(1.0f + fast_exp2(-x * LOG2E)); }
; __device__ __forceinline__ int crow(int r, int hi) { return (r & 3) + 8 * (r >> 2) + 4 * hi; }
; __device__ __forceinline__ void rglru_unit(const Params& P, int l, int unit, LAS unsigned char* lds, bool dry = false) {
;     ...
;         for (int r = 0; r < 16; ++r) { const int tok = 32 * tb + crow(r, hi);
;             const float rr = sigmoidf_(accr[r] + br), ii = sigmoidf_(acci[r] + bi);
;             const float la = -rr * sp8; const float a = fast_exp2(la * LOG2E);
;             const float x2 = 2.0f * la;
;             const float em = -x2 * (1.0f + x2 * (0.5f + x2 * (0.16666667f + x2 * (0.041666668f + x2 * (0.0083333338f + x2 * 0.0013888889f)))));
;             const float mult = __builtin_sqrtf(fmaxf(em, 0.f));
;             const float xcv = bf2f(*(const LAS unsigned short*)(xc + tok * 272 + dch * 2));
;             Ab[tok * 64 + 32 * cb + r32] = a; Ub[tok * 64 + 32 * cb + r32] = mult * ii * xcv; }
;         __syncthreads();
	v_lshlrev_b32_e32 v6, 16, v209
	v_sqrt_f32_e32 v4, v4
	v_add_f32_e32 v5, v128, v26
	v_mul_f32_e32 v5, 0xbfb8aa3b, v5
	v_exp_f32_e32 v5, v5
	v_mul_f32_e32 v2, v2, v4
	v_add_f32_e32 v4, v129, v10
	v_mul_f32_e32 v4, 0xbfb8aa3b, v4
	v_add_f32_e32 v3, 1.0, v5
	v_rcp_f32_e64 v3, -v3
	v_exp_f32_e32 v4, v4
	v_mul_f32_e32 v2, v2, v6
	ds_write_b32 v149, v2
	v_mul_f32_e32 v3, v130, v3
	v_add_f32_e32 v2, 1.0, v4
	v_add_f32_e32 v4, v3, v3
	v_fmamk_f32 v5, v4, 0x3ab60b61, v218
	v_fmaak_f32 v5, v4, v5, 0x3d2aaaab
	v_fmaak_f32 v5, v4, v5, 0x3e2aaaab
	v_fma_f32 v5, v4, v5, 0.5
	v_fma_f32 v5, v4, v5, 1.0
	v_mul_f32_e64 v4, v5, -v4
	v_max_f32_e32 v4, 0, v4
	v_mul_f32_e32 v3, 0x3fb8aa3b, v3
	v_rcp_f32_e32 v2, v2
	v_exp_f32_e32 v3, v3
	s_nop 0
	ds_read_u16 v6, v193 offset:4352
	ds_read_u16 v7, v193 offset:4624
	ds_read_u16 v8, v193 offset:4896
	ds_read_u16 v9, v193 offset:5168
	ds_read_u16 v10, v193 offset:6528
	ds_read_u16 v18, v193 offset:6800
	ds_read_u16 v19, v193 offset:7072
	ds_read_u16 v20, v193 offset:7344
	v_sqrt_f32_e32 v4, v4
	v_add_f32_e32 v5, v128, v27
	v_mul_f32_e32 v5, 0xbfb8aa3b, v5
	v_exp_f32_e32 v5, v5
	ds_write_b32 v150, v3 offset:34816
	v_mul_f32_e32 v2, v2, v4
	v_add_f32_e32 v4, v129, v11
	v_add_f32_e32 v3, 1.0, v5
	v_mul_f32_e32 v4, 0xbfb8aa3b, v4
	v_rcp_f32_e64 v3, -v3
	v_exp_f32_e32 v4, v4
	s_waitcnt lgkmcnt(8)
	v_lshlrev_b32_e32 v6, 16, v6
	v_mul_f32_e32 v2, v2, v6
	v_mul_f32_e32 v3, v130, v3
	ds_write_b32 v151, v2
	v_add_f32_e32 v2, 1.0, v4
	v_add_f32_e32 v4, v3, v3
	v_fmamk_f32 v5, v4, 0x3ab60b61, v218
	v_fmaak_f32 v5, v4, v5, 0x3d2aaaab
	v_fmaak_f32 v5, v4, v5, 0x3e2aaaab
	v_fma_f32 v5, v4, v5, 0.5
	v_fma_f32 v5, v4, v5, 1.0
	v_mul_f32_e64 v4, v5, -v4
	v_max_f32_e32 v4, 0, v4
	v_mul_f32_e32 v3, 0x3fb8aa3b, v3
	v_rcp_f32_e32 v2, v2
	v_exp_f32_e32 v3, v3
	ds_write_b32 v152, v3 offset:34816
	s_waitcnt lgkmcnt(9)
	v_lshlrev_b32_e32 v6, 16, v7
	v_sqrt_f32_e32 v4, v4
	v_add_f32_e32 v5, v128, v28
	v_mul_f32_e32 v5, 0xbfb8aa3b, v5
	v_exp_f32_e32 v5, v5
	v_mul_f32_e32 v2, v2, v4
	v_add_f32_e32 v4, v129, v12
	v_mul_f32_e32 v4, 0xbfb8aa3b, v4
	v_add_f32_e32 v3, 1.0, v5
	v_rcp_f32_e64 v3, -v3
	v_exp_f32_e32 v4, v4
	v_mul_f32_e32 v2, v2, v6
	ds_write_b32 v153, v2
	v_mul_f32_e32 v3, v130, v3
	v_add_f32_e32 v2, 1.0, v4
	v_add_f32_e32 v4, v3, v3
	v_fmamk_f32 v5, v4, 0x3ab60b61, v218
	v_fmaak_f32 v5, v4, v5, 0x3d2aaaab
	v_fmaak_f32 v5, v4, v5, 0x3e2aaaab
	v_fma_f32 v5, v4, v5, 0.5
	v_fma_f32 v5, v4, v5, 1.0
	v_mul_f32_e64 v4, v5, -v4
	v_max_f32_e32 v4, 0, v4
	v_mul_f32_e32 v3, 0x3fb8aa3b, v3
	v_rcp_f32_e32 v2, v2
	v_exp_f32_e32 v3, v3
	ds_write_b32 v154, v3 offset:34816
	s_waitcnt lgkmcnt(10)
	v_lshlrev_b32_e32 v6, 16, v8
	v_sqrt_f32_e32 v4, v4
	v_add_f32_e32 v5, v128, v29
	v_mul_f32_e32 v5, 0xbfb8aa3b, v5
	v_exp_f32_e32 v5, v5
	v_mul_f32_e32 v2, v2, v4
	v_add_f32_e32 v4, v129, v13
	v_mul_f32_e32 v4, 0xbfb8aa3b, v4
	v_add_f32_e32 v3, 1.0, v5
	v_rcp_f32_e64 v3, -v3
	v_exp_f32_e32 v4, v4
	v_mul_f32_e32 v2, v2, v6
	ds_write_b32 v155, v2
	v_mul_f32_e32 v3, v130, v3
	v_add_f32_e32 v2, 1.0, v4
	v_add_f32_e32 v4, v3, v3
	v_fmamk_f32 v5, v4, 0x3ab60b61, v218
	v_fmaak_f32 v5, v4, v5, 0x3d2aaaab
	v_fmaak_f32 v5, v4, v5, 0x3e2aaaab
	v_fma_f32 v5, v4, v5, 0.5
	v_fma_f32 v5, v4, v5, 1.0
	v_mul_f32_e64 v4, v5, -v4
	v_max_f32_e32 v4, 0, v4
	v_mul_f32_e32 v3, 0x3fb8aa3b, v3
	v_rcp_f32_e32 v2, v2
	v_exp_f32_e32 v3, v3
	ds_write_b32 v156, v3 offset:34816
	s_waitcnt lgkmcnt(11)
	v_lshlrev_b32_e32 v6, 16, v9
	v_sqrt_f32_e32 v4, v4
	v_add_f32_e32 v5, v128, v30
	v_mul_f32_e32 v5, 0xbfb8aa3b, v5
	v_exp_f32_e32 v5, v5
	v_mul_f32_e32 v2, v2, v4
	v_add_f32_e32 v4, v129, v14
	v_mul_f32_e32 v4, 0xbfb8aa3b, v4
	v_add_f32_e32 v3, 1.0, v5
	v_rcp_f32_e64 v3, -v3
	v_exp_f32_e32 v4, v4
	v_mul_f32_e32 v2, v2, v6
	ds_write_b32 v157, v2
	v_mul_f32_e32 v3, v130, v3
	v_add_f32_e32 v2, 1.0, v4
	v_add_f32_e32 v4, v3, v3
	v_fmamk_f32 v5, v4, 0x3ab60b61, v218
	v_fmaak_f32 v5, v4, v5, 0x3d2aaaab
	v_fmaak_f32 v5, v4, v5, 0x3e2aaaab
	v_fma_f32 v5, v4, v5, 0.5
	v_fma_f32 v5, v4, v5, 1.0
	v_mul_f32_e64 v4, v5, -v4
	v_max_f32_e32 v4, 0, v4
	v_mul_f32_e32 v3, 0x3fb8aa3b, v3
	v_rcp_f32_e32 v2, v2
	v_exp_f32_e32 v3, v3
	ds_write_b32 v158, v3 offset:34816
	s_waitcnt lgkmcnt(12)
	v_lshlrev_b32_e32 v6, 16, v10
	v_sqrt_f32_e32 v4, v4
	v_add_f32_e32 v5, v128, v31
	v_mul_f32_e32 v5, 0xbfb8aa3b, v5
	v_exp_f32_e32 v5, v5
	v_mul_f32_e32 v2, v2, v4
	v_add_f32_e32 v4, v129, v15
	v_mul_f32_e32 v4, 0xbfb8aa3b, v4
	v_add_f32_e32 v3, 1.0, v5
	v_rcp_f32_e64 v3, -v3
	v_exp_f32_e32 v4, v4
	v_mul_f32_e32 v2, v2, v6
	ds_write_b32 v159, v2
	v_mul_f32_e32 v3, v130, v3
	v_add_f32_e32 v2, 1.0, v4
	v_add_f32_e32 v4, v3, v3
	v_fmamk_f32 v5, v4, 0x3ab60b61, v218
	v_fmaak_f32 v5, v4, v5, 0x3d2aaaab
	v_fmaak_f32 v5, v4, v5, 0x3e2aaaab
	v_fma_f32 v5, v4, v5, 0.5
	v_fma_f32 v5, v4, v5, 1.0
	v_mul_f32_e64 v4, v5, -v4
	v_max_f32_e32 v4, 0, v4
	v_mul_f32_e32 v3, 0x3fb8aa3b, v3
	v_rcp_f32_e32 v2, v2
	v_exp_f32_e32 v3, v3
	ds_write_b32 v160, v3 offset:34816
	s_waitcnt lgkmcnt(13)
	v_lshlrev_b32_e32 v6, 16, v18
	v_sqrt_f32_e32 v4, v4
	v_add_f32_e32 v5, v128, v32
	v_mul_f32_e32 v5, 0xbfb8aa3b, v5
	v_exp_f32_e32 v5, v5
	v_mul_f32_e32 v2, v2, v4
	v_add_f32_e32 v4, v129, v16
	v_mul_f32_e32 v4, 0xbfb8aa3b, v4
	v_add_f32_e32 v3, 1.0, v5
	v_rcp_f32_e64 v3, -v3
	v_exp_f32_e32 v4, v4
	v_mul_f32_e32 v2, v2, v6
	ds_write_b32 v161, v2
	v_mul_f32_e32 v3, v130, v3
	v_add_f32_e32 v2, 1.0, v4
	v_add_f32_e32 v4, v3, v3
	v_fmamk_f32 v5, v4, 0x3ab60b61, v218
	v_fmaak_f32 v5, v4, v5, 0x3d2aaaab
	v_fmaak_f32 v5, v4, v5, 0x3e2aaaab
	v_fma_f32 v5, v4, v5, 0.5
	v_fma_f32 v5, v4, v5, 1.0
	v_mul_f32_e64 v4, v5, -v4
	v_max_f32_e32 v4, 0, v4
	v_mul_f32_e32 v3, 0x3fb8aa3b, v3
	v_rcp_f32_e32 v2, v2
	v_exp_f32_e32 v3, v3
	ds_write_b32 v162, v3 offset:34816
	s_waitcnt lgkmcnt(14)
	v_lshlrev_b32_e32 v6, 16, v19
	v_sqrt_f32_e32 v4, v4
	v_add_f32_e32 v5, v128, v33
	v_mul_f32_e32 v5, 0xbfb8aa3b, v5
	v_exp_f32_e32 v5, v5
	v_mul_f32_e32 v2, v2, v4
	v_add_f32_e32 v4, v129, v17
	v_mul_f32_e32 v4, 0xbfb8aa3b, v4
	v_add_f32_e32 v3, 1.0, v5
	v_rcp_f32_e64 v3, -v3
	v_exp_f32_e32 v4, v4
	v_mul_f32_e32 v2, v2, v6
	ds_write_b32 v163, v2
	v_mul_f32_e32 v3, v130, v3
	v_add_f32_e32 v2, 1.0, v4
	v_add_f32_e32 v4, v3, v3
	v_fmamk_f32 v5, v4, 0x3ab60b61, v218
	v_fmaak_f32 v5, v4, v5, 0x3d2aaaab
	v_fmaak_f32 v5, v4, v5, 0x3e2aaaab
	v_fma_f32 v5, v4, v5, 0.5
	v_fma_f32 v5, v4, v5, 1.0
	v_mul_f32_e64 v4, v5, -v4
	v_max_f32_e32 v4, 0, v4
	v_rcp_f32_e32 v2, v2
	v_mul_f32_e32 v3, 0x3fb8aa3b, v3
	v_exp_f32_e32 v3, v3
	ds_write_b32 v164, v3 offset:34816
	s_nop 1
	v_sqrt_f32_e32 v4, v4
	s_waitcnt lgkmcnt(14)
	v_lshlrev_b32_e32 v5, 16, v20
	v_mul_f32_e32 v2, v2, v4
	v_mul_f32_e32 v2, v2, v5
	ds_write_b32 v165, v2
	s_waitcnt lgkmcnt(0)
	s_barrier
; __device__ __forceinline__ void rglru_unit(const Params& P, int l, int unit, LAS unsigned char* lds, bool dry = false) {
;     ...
;           float As = 1.f, Hs = 0.f;
; #pragma unroll
;           for (int k = 0; k < 16; ++k) { const float a = Ab[(16 * s + k) * 64 + c], u = Ub[(16 * s + k) * 64 + c]; Hs = a * Hs + u; As *= a; }
;           seg[s * 64 + c] = (f32x2){As, Hs};
;           __syncthreads();
	ds_read2st64_b32 v[2:3], v133 offset0:136 offset1:137
	ds_read2st64_b32 v[4:5], v133 offset0:138 offset1:139
	ds_read2st64_b32 v[6:7], v133 offset0:140 offset1:141
	ds_read2st64_b32 v[8:9], v133 offset0:142 offset1:143
	ds_read_b32 v10, v166
	ds_read_b32 v11, v167
	ds_read_b32 v12, v168
	ds_read_b32 v13, v169
	ds_read_b32 v14, v170
	ds_read_b32 v15, v171
	ds_read_b32 v16, v172
	ds_read_b32 v18, v173
	s_waitcnt lgkmcnt(7)
	v_fmac_f32_e32 v10, 0, v2
	s_waitcnt lgkmcnt(6)
	v_fmac_f32_e32 v11, v10, v3
	s_waitcnt lgkmcnt(5)
	v_fmac_f32_e32 v12, v11, v4
	s_waitcnt lgkmcnt(4)
	v_fmac_f32_e32 v13, v12, v5
	s_waitcnt lgkmcnt(3)
	v_fmac_f32_e32 v14, v13, v6
	s_waitcnt lgkmcnt(2)
	v_fmac_f32_e32 v15, v14, v7
	s_waitcnt lgkmcnt(1)
	v_fmac_f32_e32 v16, v15, v8
	v_mul_f32_e32 v2, v2, v3
	s_waitcnt lgkmcnt(0)
	v_fmac_f32_e32 v18, v16, v9
	ds_read2st64_b32 v[10:11], v133 offset0:144 offset1:145
	ds_read2st64_b32 v[12:13], v133 offset0:146 offset1:147
	ds_read2st64_b32 v[14:15], v133 offset0:148 offset1:149
	ds_read2st64_b32 v[16:17], v133 offset0:150 offset1:151
	ds_read_b32 v3, v174
	ds_read_b32 v19, v175
	ds_read_b32 v21, v176
	ds_read_b32 v23, v177
	ds_read_b32 v25, v178
	ds_read_b32 v27, v179
	ds_read_b32 v29, v186
	ds_read_b32 v31, v187
	s_waitcnt lgkmcnt(7)
	v_fmac_f32_e32 v3, v18, v10
	v_mov_b32_e32 v32, v4
	v_mov_b32_e32 v33, v11
	v_mov_b32_e32 v18, v5
	v_mul_f32_e32 v4, v2, v4
	s_waitcnt lgkmcnt(6)
	v_pk_fma_f32 v[2:3], v[2:3], v[32:33], v[18:19]
	v_mul_f32_e32 v4, v4, v5
	v_mov_b32_e32 v5, v3
	v_mov_b32_e32 v2, v6
	v_mov_b32_e32 v3, v12
	v_pk_mul_f32 v[18:19], v[4:5], v[2:3]
	v_mov_b32_e32 v6, v7
	v_mov_b32_e32 v20, v7
	v_pk_mul_f32 v[6:7], v[18:19], v[6:7]
	s_waitcnt lgkmcnt(5)
	v_pk_fma_f32 v[2:3], v[4:5], v[2:3], v[20:21]
	v_mov_b32_e32 v4, v8
	v_mov_b32_e32 v2, v6
	v_mov_b32_e32 v5, v13
	v_pk_mul_f32 v[6:7], v[6:7], v[8:9]
	v_mov_b32_e32 v8, v9
	v_mov_b32_e32 v22, v9
	v_pk_mul_f32 v[6:7], v[6:7], v[8:9]
	s_waitcnt lgkmcnt(4)
	v_pk_fma_f32 v[2:3], v[2:3], v[4:5], v[22:23]
	v_mov_b32_e32 v8, v11
	v_mov_b32_e32 v7, v3
	v_mov_b32_e32 v2, v10
	v_mov_b32_e32 v3, v14
	v_pk_mul_f32 v[4:5], v[6:7], v[2:3]
	v_mov_b32_e32 v24, v11
	v_pk_mul_f32 v[4:5], v[4:5], v[8:9]
	s_waitcnt lgkmcnt(3)
	v_pk_fma_f32 v[2:3], v[6:7], v[2:3], v[24:25]
	v_mov_b32_e32 v6, v12
	v_mov_b32_e32 v2, v4
	v_mov_b32_e32 v7, v15
	v_pk_mul_f32 v[4:5], v[4:5], v[12:13]
	v_mov_b32_e32 v8, v13
	v_mov_b32_e32 v26, v13
	v_pk_mul_f32 v[4:5], v[4:5], v[8:9]
	s_waitcnt lgkmcnt(2)
	v_pk_fma_f32 v[2:3], v[2:3], v[6:7], v[26:27]
	v_mov_b32_e32 v8, v15
	v_mov_b32_e32 v5, v3
	v_mov_b32_e32 v2, v14
	v_mov_b32_e32 v3, v16
	v_pk_mul_f32 v[6:7], v[4:5], v[2:3]
	v_mov_b32_e32 v28, v15
	v_pk_mul_f32 v[6:7], v[6:7], v[8:9]
	s_waitcnt lgkmcnt(1)
	v_pk_fma_f32 v[2:3], v[4:5], v[2:3], v[28:29]
	v_pk_mul_f32 v[4:5], v[6:7], v[16:17]
	v_mov_b32_e32 v2, v6
	v_mov_b32_e32 v6, v17
	v_mov_b32_e32 v30, v17
	v_pk_mul_f32 v[4:5], v[4:5], v[6:7]
	s_waitcnt lgkmcnt(0)
	v_pk_fma_f32 v[2:3], v[2:3], v[16:17], v[30:31]
	s_nop 0
	v_mov_b32_e32 v5, v3
	ds_write_b64 v131, v[4:5]
	s_waitcnt lgkmcnt(0)
	s_barrier
; __device__ __forceinline__ unsigned f2bf(float f) { unsigned u = __builtin_bit_cast(unsigned, f); return (u + 0x7fffu + ((u >> 16) & 1u)) >> 16; }
; __device__ __forceinline__ void rglru_unit(const Params& P, int l, int unit, LAS unsigned char* lds, bool dry = false) {
;     ...
;           float hin = carry, hn = carry;
; #pragma unroll
;           for (int s2 = 0; s2 < 8; ++s2) { if (s2 == s) hin = hn; const f32x2 sg = seg[s2 * 64 + c]; hn = sg.x * hn + sg.y; }
;           carry = hn;
;           float h = hin;
; #pragma unroll
;           for (int k = 0; k < 16; ++k) { const float a = Ab[(16 * s + k) * 64 + c], u = Ub[(16 * s + k) * 64 + c]; h = a * h + u;
;               const float gg = bf2f(gq[k]); gp[(size_t)k * XP] = (bf16_t)f2bf(dry ? gg : gg * h); }
	ds_read2st64_b64 v[2:5], v132 offset1:1
	ds_read2st64_b64 v[6:9], v132 offset0:2 offset1:3
	s_waitcnt lgkmcnt(1)
	v_fma_f32 v2, v89, v2, v3
	v_cndmask_b32_e64 v3, v89, v2, s[6:7]
	v_fmac_f32_e32 v5, v4, v2
	v_cndmask_b32_e64 v10, v3, v5, s[8:9]
	s_waitcnt lgkmcnt(0)
	v_fma_f32 v6, v6, v5, v7
	ds_read2st64_b64 v[2:5], v132 offset0:4 offset1:5
	ds_read2st64_b64 v[86:89], v132 offset0:6 offset1:7
	v_cndmask_b32_e64 v7, v10, v6, s[10:11]
	v_fmac_f32_e32 v9, v8, v6
	v_cndmask_b32_e64 v6, v7, v9, s[12:13]
	s_waitcnt lgkmcnt(1)
	v_fma_f32 v2, v2, v9, v3
	v_cndmask_b32_e64 v3, v6, v2, s[14:15]
	v_fmac_f32_e32 v5, v4, v2
	v_cndmask_b32_e64 v2, v3, v5, s[16:17]
	s_waitcnt lgkmcnt(0)
	v_fma_f32 v10, v86, v5, v87
	v_cndmask_b32_e64 v11, v2, v10, s[18:19]
	ds_read2st64_b32 v[2:3], v133 offset0:136 offset1:137
	ds_read2st64_b32 v[4:5], v133 offset0:138 offset1:139
	ds_read2st64_b32 v[6:7], v133 offset0:140 offset1:141
	ds_read2st64_b32 v[8:9], v133 offset0:142 offset1:143
	ds_read_b32 v12, v166
	ds_read_b32 v13, v167
	ds_read_b32 v14, v168
	ds_read_b32 v15, v169
	ds_read_b32 v16, v170
	ds_read_b32 v17, v171
	ds_read_b32 v18, v172
	ds_read_b32 v19, v173
	s_waitcnt lgkmcnt(7)
	v_fmac_f32_e32 v12, v2, v11
	s_waitcnt vmcnt(0)
	v_lshlrev_b32_e32 v1, 16, v1
	v_lshlrev_b32_e32 v2, 16, v207
	v_mul_f32_e32 v2, v12, v2
	v_bfe_u32 v11, v2, 16, 1
	v_add3_u32 v2, v2, v11, s60
	global_store_short_d16_hi v[126:127], v2, off
	s_waitcnt lgkmcnt(0)
	v_fmac_f32_e32 v13, v3, v12
	v_lshlrev_b32_e32 v2, 16, v206
	v_mul_f32_e32 v2, v13, v2
	v_bfe_u32 v3, v2, 16, 1
	v_add3_u32 v2, v2, v3, s60
	global_store_short_d16_hi v[126:127], v2, off offset:2048
	v_fmac_f32_e32 v14, v4, v13
	v_lshlrev_b32_e32 v2, 16, v205
	v_mul_f32_e32 v2, v14, v2
	v_bfe_u32 v3, v2, 16, 1
	v_add3_u32 v2, v2, v3, s60
	global_store_short_d16_hi v[124:125], v2, off
	v_fmac_f32_e32 v15, v5, v14
	v_lshlrev_b32_e32 v2, 16, v204
	v_mul_f32_e32 v2, v15, v2
	v_bfe_u32 v3, v2, 16, 1
	v_add3_u32 v2, v2, v3, s60
	global_store_short_d16_hi v[124:125], v2, off offset:2048
	v_fmac_f32_e32 v16, v6, v15
	v_lshlrev_b32_e32 v2, 16, v203
	v_mul_f32_e32 v2, v16, v2
	v_bfe_u32 v3, v2, 16, 1
	v_add3_u32 v2, v2, v3, s60
	global_store_short_d16_hi v[122:123], v2, off
	v_fmac_f32_e32 v17, v7, v16
	v_lshlrev_b32_e32 v2, 16, v202
	v_mul_f32_e32 v2, v17, v2
	v_bfe_u32 v3, v2, 16, 1
	v_add3_u32 v2, v2, v3, s60
	global_store_short_d16_hi v[122:123], v2, off offset:2048
	v_fmac_f32_e32 v18, v8, v17
	v_lshlrev_b32_e32 v2, 16, v201
	v_mul_f32_e32 v2, v18, v2
	v_bfe_u32 v3, v2, 16, 1
	v_add3_u32 v2, v2, v3, s60
	global_store_short_d16_hi v[120:121], v2, off
	v_fmac_f32_e32 v19, v9, v18
	v_lshlrev_b32_e32 v2, 16, v200
	v_mul_f32_e32 v2, v19, v2
	v_bfe_u32 v3, v2, 16, 1
	v_add3_u32 v2, v2, v3, s60
	global_store_short_d16_hi v[120:121], v2, off offset:2048
	ds_read2st64_b32 v[2:3], v133 offset0:144 offset1:145
	ds_read2st64_b32 v[4:5], v133 offset0:146 offset1:147
	ds_read2st64_b32 v[6:7], v133 offset0:148 offset1:149
	ds_read2st64_b32 v[8:9], v133 offset0:150 offset1:151
	ds_read_b32 v11, v174
	ds_read_b32 v12, v175
	ds_read_b32 v13, v176
	ds_read_b32 v14, v177
	ds_read_b32 v15, v178
	ds_read_b32 v16, v179
	ds_read_b32 v17, v186
	ds_read_b32 v18, v187
	s_waitcnt lgkmcnt(0)
	v_fmac_f32_e32 v11, v19, v2
	v_lshlrev_b32_e32 v2, 16, v199
	v_mul_f32_e32 v2, v11, v2
	v_bfe_u32 v19, v2, 16, 1
	v_add3_u32 v2, v2, v19, s60
	global_store_short_d16_hi v[118:119], v2, off
	v_fmac_f32_e32 v12, v11, v3
	v_lshlrev_b32_e32 v2, 16, v198
	v_mul_f32_e32 v2, v12, v2
	v_bfe_u32 v3, v2, 16, 1
	v_add3_u32 v2, v2, v3, s60
	global_store_short_d16_hi v[118:119], v2, off offset:2048
	v_fmac_f32_e32 v13, v12, v4
	v_lshlrev_b32_e32 v2, 16, v197
	v_mul_f32_e32 v2, v13, v2
	v_bfe_u32 v3, v2, 16, 1
	v_add3_u32 v2, v2, v3, s60
	global_store_short_d16_hi v[116:117], v2, off
	v_fmac_f32_e32 v14, v13, v5
	v_lshlrev_b32_e32 v2, 16, v196
	v_mul_f32_e32 v2, v14, v2
	v_bfe_u32 v3, v2, 16, 1
	v_add3_u32 v2, v2, v3, s60
	global_store_short_d16_hi v[116:117], v2, off offset:2048
	v_fmac_f32_e32 v15, v14, v6
	v_lshlrev_b32_e32 v2, 16, v195
	v_mul_f32_e32 v2, v15, v2
	v_bfe_u32 v3, v2, 16, 1
	v_add3_u32 v2, v2, v3, s60
	global_store_short_d16_hi v[114:115], v2, off
	v_fmac_f32_e32 v16, v15, v7
	v_lshlrev_b32_e32 v2, 16, v194
	v_mul_f32_e32 v2, v16, v2
	v_bfe_u32 v3, v2, 16, 1
	v_add3_u32 v2, v2, v3, s60
	global_store_short_d16_hi v[114:115], v2, off offset:2048
	v_fmac_f32_e32 v17, v16, v8
	v_lshlrev_b32_e32 v2, 16, v111
	v_mul_f32_e32 v2, v17, v2
	v_bfe_u32 v3, v2, 16, 1
	v_fmac_f32_e32 v18, v17, v9
	v_add3_u32 v2, v2, v3, s60
	v_mul_f32_e32 v1, v18, v1
	global_store_short_d16_hi v[112:113], v2, off
	v_bfe_u32 v2, v1, 16, 1
	v_add3_u32 v1, v1, v2, s60
	v_fmac_f32_e32 v89, v88, v10
	global_store_short_d16_hi v[112:113], v1, off offset:2048
	s_cbranch_scc0 .LBB0_346
